# v68 + two 4-byte pads: only the P1 main loop head moves from 4 to 0 mod 8 bytes
# speedup vs baseline: 1.0066x; 1.0066x over previous
.LBB0_125:
	s_nop 0
	s_add_u32 s48, s52, 0x2000000
	s_addc_u32 s49, s53, 0
	s_add_u32 s28, s52, 0x8000000
	s_addc_u32 s29, s53, 0
	s_add_u32 s18, s52, 0x1a00000
	s_addc_u32 s19, s53, 0
	s_add_u32 s36, s52, 0x1b00000
	s_addc_u32 s37, s53, 0
	s_add_u32 s20, s52, 0x1c00000
	s_addc_u32 s21, s53, 0
	v_mov_b32_e32 v10, v196
	s_cmpk_lt_i32 s2, 0x400
	s_cselect_b64 s[88:89], -1, 0
	s_cmpk_gt_i32 s2, 0x3ff
	v_readfirstlane_b32 s5, v10
	s_cbranch_scc1 .LBB0_161
	s_ashr_i32 s3, s2, 31
	s_lshr_b32 s0, s3, 29
	s_add_i32 s6, s2, s0
	s_and_b32 s0, s6, -8
	s_sub_i32 s7, s2, s0
	s_cmp_gt_i32 s7, -1
	s_cbranch_scc0 .LBB0_128
	s_lshl_b32 s4, s7, 7
	s_mov_b64 s[0:1], 0
	s_branch .LBB0_129
